# GDN scan: finalizer waves issue all LDS-DMA staging right after the step barrier, MFMA waves none
# baseline (speedup 1.0000x reference)
.LBB0_443:
	s_waitcnt vmcnt(0)
	s_waitcnt lgkmcnt(0)
	s_barrier
	s_andn2_b64 vcc, exec, s[22:23]
	s_cbranch_vccnz .LBB0_445
	s_add_i32 s58, s29, 1
	s_cmpk_lg_i32 s56, 0xfc0
	s_cselect_b32 s31, s58, 63
	s_add_u32 s38, s34, s31
	s_addc_u32 s39, s35, 0
	v_mov_b32_e32 v106, v180
	s_bitcmp1_b32 s57, 0
	v_ashrrev_i32_e32 v107, 4, v106
	v_add_u32_e32 v2, s52, v107
	s_cselect_b32 s0, 0xe000, 0
	v_xor_b32_e32 v4, v2, v106
	s_add_i32 s37, s27, s0
	v_ashrrev_i32_e32 v108, 3, v106
	s_lshl_b64 s[0:1], s[38:39], 13
	s_lshl_b64 s[60:61], s[38:39], 14
	v_lshlrev_b32_e32 v2, 7, v2
	v_lshlrev_b32_e32 v4, 3, v4
	s_add_u32 s62, s43, s60
	v_and_or_b32 v2, v4, s50, v2
	v_add_u32_e32 v4, s53, v108
	s_addc_u32 s63, s44, s61
	v_lshrrev_b32_e32 v5, 1, v4
	s_add_u32 s64, s15, s60
	v_xor_b32_e32 v5, v5, v106
	s_addc_u32 s65, s19, s61
	s_add_i32 s59, s37, 0x4000
	v_lshlrev_b32_e32 v4, 6, v4
	v_lshlrev_b32_e32 v5, 3, v5
	v_lshlrev_b64 v[102:103], 1, v[2:3]
	s_add_u32 s60, s45, s60
	v_and_or_b32 v4, v5, 56, v4
	v_lshl_add_u64 v[104:105], s[62:63], 0, v[102:103]
	s_mov_b32 m0, s37
	v_mov_b32_e32 v5, v3
	s_addc_u32 s61, s46, s61
	s_add_i32 s66, s37, 0x8000
	global_load_lds_dwordx4 v[104:105], off
	v_lshl_add_u64 v[102:103], s[64:65], 0, v[102:103]
	s_mov_b32 m0, s59
	v_lshlrev_b64 v[4:5], 1, v[4:5]
	global_load_lds_dwordx4 v[102:103], off
	v_lshl_add_u64 v[102:103], s[60:61], 0, v[4:5]
	s_mov_b32 m0, s66
	v_add_u32_e32 v2, s54, v107
	global_load_lds_dwordx4 v[102:103], off
	v_xor_b32_e32 v102, v2, v106
	v_lshlrev_b32_e32 v2, 7, v2
	v_lshlrev_b32_e32 v102, 3, v102
	v_and_or_b32 v2, v102, s50, v2
	v_add_u32_e32 v102, s55, v108
	v_lshrrev_b32_e32 v103, 1, v102
	v_lshlrev_b64 v[104:105], 1, v[2:3]
	v_xor_b32_e32 v103, v103, v106
	v_lshl_add_u64 v[106:107], s[62:63], 0, v[104:105]
	s_add_i32 m0, s37, 0x2000
	v_lshlrev_b32_e32 v102, 6, v102
	v_lshlrev_b32_e32 v103, 3, v103
	global_load_lds_dwordx4 v[106:107], off
	v_lshl_add_u64 v[104:105], s[64:65], 0, v[104:105]
	s_add_i32 m0, s37, 0x6000
	v_and_or_b32 v102, v103, 56, v102
	global_load_lds_dwordx4 v[104:105], off
	v_mov_b32_e32 v103, v3
	s_add_i32 m0, s37, 0xa000
	v_lshl_add_u64 v[102:103], v[102:103], 1, s[60:61]
	s_add_u32 s0, s33, s0
	global_load_lds_dwordx4 v[102:103], off
	s_addc_u32 s1, s40, s1
	s_add_i32 m0, s37, 0xc000
	v_lshl_add_u64 v[4:5], s[0:1], 0, v[4:5]
	s_nop 0
	global_load_lds_dwordx4 v[4:5], off
	s_sub_i32 s52, s52, 16
	s_sub_i32 s53, s53, 32
	s_sub_i32 s54, s54, 16
	s_sub_i32 s55, s55, 32
	s_sub_i32 s27, s27, 0x1000
	v_mov_b32_e32 v106, v180
	s_bitcmp1_b32 s57, 0
	v_ashrrev_i32_e32 v107, 4, v106
	v_add_u32_e32 v2, s52, v107
	s_cselect_b32 s0, 0xe000, 0
	v_xor_b32_e32 v4, v2, v106
	s_add_i32 s37, s27, s0
	v_ashrrev_i32_e32 v108, 3, v106
	s_lshl_b64 s[0:1], s[38:39], 13
	s_lshl_b64 s[60:61], s[38:39], 14
	v_lshlrev_b32_e32 v2, 7, v2
	v_lshlrev_b32_e32 v4, 3, v4
	s_add_u32 s62, s43, s60
	v_and_or_b32 v2, v4, s50, v2
	v_add_u32_e32 v4, s53, v108
	s_addc_u32 s63, s44, s61
	v_lshrrev_b32_e32 v5, 1, v4
	s_add_u32 s64, s15, s60
	v_xor_b32_e32 v5, v5, v106
	s_addc_u32 s65, s19, s61
	s_add_i32 s59, s37, 0x4000
	v_lshlrev_b32_e32 v4, 6, v4
	v_lshlrev_b32_e32 v5, 3, v5
	v_lshlrev_b64 v[102:103], 1, v[2:3]
	s_add_u32 s60, s45, s60
	v_and_or_b32 v4, v5, 56, v4
	v_lshl_add_u64 v[104:105], s[62:63], 0, v[102:103]
	s_mov_b32 m0, s37
	v_mov_b32_e32 v5, v3
	s_addc_u32 s61, s46, s61
	s_add_i32 s66, s37, 0x8000
	global_load_lds_dwordx4 v[104:105], off
	v_lshl_add_u64 v[102:103], s[64:65], 0, v[102:103]
	s_mov_b32 m0, s59
	v_lshlrev_b64 v[4:5], 1, v[4:5]
	global_load_lds_dwordx4 v[102:103], off
	v_lshl_add_u64 v[102:103], s[60:61], 0, v[4:5]
	s_mov_b32 m0, s66
	v_add_u32_e32 v2, s54, v107
	global_load_lds_dwordx4 v[102:103], off
	v_xor_b32_e32 v102, v2, v106
	v_lshlrev_b32_e32 v2, 7, v2
	v_lshlrev_b32_e32 v102, 3, v102
	v_and_or_b32 v2, v102, s50, v2
	v_add_u32_e32 v102, s55, v108
	v_lshrrev_b32_e32 v103, 1, v102
	v_lshlrev_b64 v[104:105], 1, v[2:3]
	v_xor_b32_e32 v103, v103, v106
	v_lshl_add_u64 v[106:107], s[62:63], 0, v[104:105]
	s_add_i32 m0, s37, 0x2000
	v_lshlrev_b32_e32 v102, 6, v102
	v_lshlrev_b32_e32 v103, 3, v103
	global_load_lds_dwordx4 v[106:107], off
	v_lshl_add_u64 v[104:105], s[64:65], 0, v[104:105]
	s_add_i32 m0, s37, 0x6000
	v_and_or_b32 v102, v103, 56, v102
	global_load_lds_dwordx4 v[104:105], off
	v_mov_b32_e32 v103, v3
	s_add_i32 m0, s37, 0xa000
	v_lshl_add_u64 v[102:103], v[102:103], 1, s[60:61]
	s_add_u32 s0, s33, s0
	global_load_lds_dwordx4 v[102:103], off
	s_addc_u32 s1, s40, s1
	s_add_i32 m0, s37, 0xc000
	v_lshl_add_u64 v[4:5], s[0:1], 0, v[4:5]
	s_nop 0
	global_load_lds_dwordx4 v[4:5], off
	s_add_i32 s52, s52, 16
	s_add_i32 s53, s53, 32
	s_add_i32 s54, s54, 16
	s_add_i32 s55, s55, 32
	s_add_i32 s27, s27, 0x1000
	s_min_u32 s0, s29, 1
	s_sub_i32 s1, s29, s0
	s_lshl_b32 s0, s0, 6
	v_subrev_u32_e32 v2, s0, v203
	s_and_b32 s0, s1, 1
	v_lshl_add_u32 v205, s0, 10, v199
	ds_read2_b32 v[4:5], v205 offset1:16
	ds_read2_b32 v[120:121], v205 offset0:128 offset1:144
	ds_read2_b32 v[122:123], v205 offset0:64 offset1:80
	ds_read2_b32 v[134:135], v205 offset0:192 offset1:208
	v_lshl_add_u32 v204, s0, 14, v182
	s_waitcnt lgkmcnt(0)
	v_mov_b32_e32 v102, v4
	v_mov_b32_e32 v103, v120
	v_mov_b32_e32 v104, v122
	v_mov_b32_e32 v105, v134
	v_add_u32_e32 v4, v204, v186
	s_waitcnt vmcnt(0)
	v_lshlrev_b32_e32 v114, 16, v170
	v_pk_add_f32 v[136:137], v[102:103], v[104:105]
	ds_read_b128 v[116:119], v4
	ds_read_b128 v[102:105], v183
	v_and_b32_e32 v115, 0xffff0000, v170
	v_mul_f32_e32 v4, 0xbfb8aa3b, v114
	v_exp_f32_e32 v4, v4
	v_mul_f32_e32 v106, 0xbfb8aa3b, v115
	v_exp_f32_e32 v110, v106
	ds_read_b128 v[106:109], v183 offset:16
	v_add_f32_e32 v4, 1.0, v4
	v_rcp_f32_e32 v124, v4
	v_add_f32_e32 v4, 1.0, v110
	v_rcp_f32_e32 v125, v4
	v_add_u32_e32 v4, v204, v188
	ds_read_b128 v[110:113], v4
	s_waitcnt lgkmcnt(3)
	v_lshlrev_b32_e32 v206, 16, v116
	v_pk_mul_f32 v[114:115], v[124:125], v[114:115]
	v_lshlrev_b32_e32 v124, 16, v171
	v_mul_f32_e32 v4, 0xbfb8aa3b, v124
	v_and_b32_e32 v125, 0xffff0000, v171
	v_and_b32_e32 v207, 0xffff0000, v116
	v_exp_f32_e32 v4, v4
	v_mul_f32_e32 v116, 0xbfb8aa3b, v125
	v_exp_f32_e32 v120, v116
	v_lshlrev_b32_e32 v128, 16, v168
	v_add_f32_e32 v4, 1.0, v4
	v_rcp_f32_e32 v126, v4
	v_add_f32_e32 v4, 1.0, v120
	v_rcp_f32_e32 v127, v4
	v_mul_f32_e32 v4, 0xbfb8aa3b, v128
	v_and_b32_e32 v129, 0xffff0000, v168
	v_exp_f32_e32 v4, v4
	v_mul_f32_e32 v120, 0xbfb8aa3b, v129
	v_exp_f32_e32 v120, v120
	v_lshlrev_b32_e32 v168, 16, v169
	v_pk_mul_f32 v[124:125], v[126:127], v[124:125]
	v_add_f32_e32 v4, 1.0, v4
	v_lshlrev_b32_e32 v126, 16, v118
	v_and_b32_e32 v127, 0xffff0000, v118
	v_and_b32_e32 v169, 0xffff0000, v169
	v_mul_f32_e32 v118, 0xbfb8aa3b, v168
	v_rcp_f32_e32 v130, v4
	v_add_f32_e32 v4, 1.0, v120
	v_exp_f32_e32 v118, v118
	v_mul_f32_e32 v120, 0xbfb8aa3b, v169
	v_exp_f32_e32 v120, v120
	v_rcp_f32_e32 v131, v4
	v_add_f32_e32 v4, 1.0, v118
	v_rcp_f32_e32 v170, v4
	v_add_f32_e32 v4, 1.0, v120
	v_mov_b32_e32 v120, v5
	v_mov_b32_e32 v134, v123
	v_pk_mul_f32 v[132:133], v[130:131], v[128:129]
	v_lshlrev_b32_e32 v130, 16, v119
	v_and_b32_e32 v131, 0xffff0000, v119
	v_pk_add_f32 v[118:119], v[120:121], v[134:135]
	v_mov_b32_e32 v121, v136
	v_mov_b32_e32 v120, v118
	v_mov_b32_e32 v136, v119
	v_pk_add_f32 v[118:119], v[120:121], v[136:137]
	v_mov_b64_e32 v[122:123], s[18:19]
	v_pk_fma_f32 v[134:135], v[118:119], s[14:15], v[122:123] op_sel_hi:[1,0,0]
	v_rcp_f32_e32 v171, v4
	v_add_u32_e32 v4, s56, v2
	v_mul_f32_e32 v2, 0x4b800000, v135
	v_cmp_gt_f32_e32 vcc, s51, v135
	v_ashrrev_i32_e32 v5, 31, v4
	v_lshlrev_b64 v[118:119], 11, v[4:5]
	v_cndmask_b32_e32 v2, v135, v2, vcc
	v_rsq_f32_e32 v2, v2
	v_pk_mul_f32 v[128:129], v[170:171], v[168:169]
	v_lshlrev_b32_e32 v116, 16, v117
	v_and_b32_e32 v117, 0xffff0000, v117
	v_mul_f32_e32 v5, 0x45800000, v2
	v_cndmask_b32_e32 v2, v2, v5, vcc
	v_pk_mul_f32 v[168:169], v[2:3], v[206:207] op_sel_hi:[0,1]
	s_waitcnt lgkmcnt(2)
	v_pk_mul_f32 v[168:169], v[102:103], v[168:169]
	v_cmp_gt_f32_e32 vcc, s51, v134
	v_pk_mul_f32 v[114:115], v[114:115], v[168:169]
	v_lshl_add_u64 v[136:137], v[150:151], 0, v[118:119]
	v_cvt_pk_bf16_f32 v168, v114, v115
	v_pk_mul_f32 v[114:115], v[2:3], v[116:117] op_sel_hi:[0,1]
	v_pk_mul_f32 v[114:115], v[104:105], v[114:115]
	ds_read_b128 v[118:121], v183
	v_pk_mul_f32 v[114:115], v[124:125], v[114:115]
	v_pk_mul_f32 v[124:125], v[2:3], v[126:127] op_sel_hi:[0,1]
	s_waitcnt lgkmcnt(2)
	v_pk_mul_f32 v[124:125], v[106:107], v[124:125]
	v_cvt_pk_bf16_f32 v169, v114, v115
	v_pk_mul_f32 v[124:125], v[132:133], v[124:125]
	ds_read_b128 v[114:117], v183 offset:16
	v_cvt_pk_bf16_f32 v170, v124, v125
	v_pk_mul_f32 v[124:125], v[2:3], v[130:131] op_sel_hi:[0,1]
	v_mul_f32_e32 v2, 0x4b800000, v134
	v_cndmask_b32_e32 v2, v134, v2, vcc
	v_rsq_f32_e32 v2, v2
	v_pk_mul_f32 v[124:125], v[108:109], v[124:125]
	v_mul_f32_e32 v5, 0x45800000, v2
	v_pk_mul_f32 v[124:125], v[128:129], v[124:125]
	v_cndmask_b32_e32 v2, v2, v5, vcc
	v_cvt_pk_bf16_f32 v171, v124, v125
	v_lshlrev_b32_e32 v124, 16, v164
	v_mul_f32_e32 v5, 0xbfb8aa3b, v124
	v_and_b32_e32 v125, 0xffff0000, v164
	v_exp_f32_e32 v5, v5
	v_mul_f32_e32 v126, 0xbfb8aa3b, v125
	v_exp_f32_e32 v127, v126
	s_waitcnt lgkmcnt(2)
	v_lshlrev_b32_e32 v128, 16, v110
	v_add_f32_e32 v5, 1.0, v5
	v_rcp_f32_e32 v126, v5
	v_add_f32_e32 v5, 1.0, v127
	v_rcp_f32_e32 v127, v5
	v_and_b32_e32 v129, 0xffff0000, v110
	v_pk_mul_f32 v[128:129], v[2:3], v[128:129] op_sel_hi:[0,1]
	v_pk_mul_f32 v[128:129], v[102:103], v[128:129]
	v_pk_mul_f32 v[124:125], v[126:127], v[124:125]
	global_store_dwordx4 v[136:137], v[168:171], off
	v_pk_mul_f32 v[124:125], v[124:125], v[128:129]
	v_lshlrev_b32_e32 v128, 16, v111
	v_cvt_pk_bf16_f32 v110, v124, v125
	v_lshlrev_b32_e32 v124, 16, v165
	v_mul_f32_e32 v5, 0xbfb8aa3b, v124
	v_and_b32_e32 v125, 0xffff0000, v165
	v_exp_f32_e32 v5, v5
	v_mul_f32_e32 v126, 0xbfb8aa3b, v125
	v_exp_f32_e32 v127, v126
	v_and_b32_e32 v129, 0xffff0000, v111
	v_add_f32_e32 v5, 1.0, v5
	v_rcp_f32_e32 v126, v5
	v_add_f32_e32 v5, 1.0, v127
	v_rcp_f32_e32 v127, v5
	v_pk_mul_f32 v[128:129], v[2:3], v[128:129] op_sel_hi:[0,1]
	v_pk_mul_f32 v[128:129], v[104:105], v[128:129]
	v_lshlrev_b32_e32 v170, 16, v156
	v_pk_mul_f32 v[124:125], v[126:127], v[124:125]
	v_and_b32_e32 v171, 0xffff0000, v156
	v_pk_mul_f32 v[124:125], v[124:125], v[128:129]
	v_lshlrev_b32_e32 v128, 16, v112
	v_cvt_pk_bf16_f32 v111, v124, v125
	v_lshlrev_b32_e32 v124, 16, v160
	v_mul_f32_e32 v5, 0xbfb8aa3b, v124
	v_and_b32_e32 v125, 0xffff0000, v160
	v_exp_f32_e32 v5, v5
	v_mul_f32_e32 v126, 0xbfb8aa3b, v125
	v_exp_f32_e32 v127, v126
	v_and_b32_e32 v129, 0xffff0000, v112
	v_add_f32_e32 v5, 1.0, v5
	v_rcp_f32_e32 v126, v5
	v_add_f32_e32 v5, 1.0, v127
	v_rcp_f32_e32 v127, v5
	v_pk_mul_f32 v[128:129], v[2:3], v[128:129] op_sel_hi:[0,1]
	v_pk_mul_f32 v[128:129], v[106:107], v[128:129]
	v_lshlrev_b32_e32 v160, 16, v158
	v_pk_mul_f32 v[124:125], v[126:127], v[124:125]
	s_nop 0
	v_pk_mul_f32 v[124:125], v[124:125], v[128:129]
	v_lshlrev_b32_e32 v128, 16, v113
	v_cvt_pk_bf16_f32 v112, v124, v125
	v_lshlrev_b32_e32 v124, 16, v161
	v_mul_f32_e32 v5, 0xbfb8aa3b, v124
	v_and_b32_e32 v125, 0xffff0000, v161
	v_exp_f32_e32 v5, v5
	v_mul_f32_e32 v126, 0xbfb8aa3b, v125
	v_exp_f32_e32 v127, v126
	v_and_b32_e32 v129, 0xffff0000, v113
	v_add_f32_e32 v5, 1.0, v5
	v_rcp_f32_e32 v126, v5
	v_add_f32_e32 v5, 1.0, v127
	v_rcp_f32_e32 v127, v5
	v_pk_mul_f32 v[128:129], v[2:3], v[128:129] op_sel_hi:[0,1]
	v_pk_mul_f32 v[128:129], v[108:109], v[128:129]
	v_and_b32_e32 v161, 0xffff0000, v158
	v_pk_mul_f32 v[124:125], v[126:127], v[124:125]
	v_mul_f32_e32 v5, 0xbfb8aa3b, v160
	v_pk_mul_f32 v[124:125], v[124:125], v[128:129]
	ds_read2_b32 v[128:129], v205 offset0:32 offset1:48
	ds_read2_b32 v[130:131], v205 offset0:160 offset1:176
	ds_read2_b32 v[132:133], v205 offset0:96 offset1:112
	ds_read2_b32 v[134:135], v205 offset0:224 offset1:240
	v_cvt_pk_bf16_f32 v113, v124, v125
	v_add_u32_e32 v124, 16, v4
	v_ashrrev_i32_e32 v125, 31, v124
	v_lshlrev_b64 v[124:125], 11, v[124:125]
	v_lshl_add_u64 v[124:125], v[150:151], 0, v[124:125]
	global_store_dwordx4 v[124:125], v[110:113], off
	v_exp_f32_e32 v5, v5
	v_add_u32_e32 v2, v204, v190
	s_waitcnt lgkmcnt(3)
	v_mov_b32_e32 v110, v128
	s_waitcnt lgkmcnt(2)
	v_mov_b32_e32 v111, v130
	s_waitcnt lgkmcnt(1)
	v_mov_b32_e32 v112, v132
	s_waitcnt lgkmcnt(0)
	v_mov_b32_e32 v113, v134
	v_pk_add_f32 v[136:137], v[110:111], v[112:113]
	v_mul_f32_e32 v110, 0xbfb8aa3b, v161
	v_exp_f32_e32 v124, v110
	ds_read_b128 v[110:113], v2
	v_add_f32_e32 v2, 1.0, v5
	v_rcp_f32_e32 v164, v2
	v_add_f32_e32 v2, 1.0, v124
	v_rcp_f32_e32 v165, v2
	v_add_u32_e32 v2, v204, v192
	v_lshlrev_b32_e32 v158, 16, v159
	ds_read_b128 v[124:127], v2
	v_mul_f32_e32 v2, 0xbfb8aa3b, v158
	v_and_b32_e32 v159, 0xffff0000, v159
	v_exp_f32_e32 v2, v2
	v_mul_f32_e32 v5, 0xbfb8aa3b, v159
	v_exp_f32_e32 v5, v5
	v_pk_mul_f32 v[160:161], v[164:165], v[160:161]
	v_add_f32_e32 v2, 1.0, v2
	v_rcp_f32_e32 v164, v2
	v_add_f32_e32 v2, 1.0, v5
	v_rcp_f32_e32 v165, v2
	v_mul_f32_e32 v2, 0xbfb8aa3b, v170
	v_exp_f32_e32 v2, v2
	v_mul_f32_e32 v5, 0xbfb8aa3b, v171
	v_exp_f32_e32 v5, v5
	v_lshlrev_b32_e32 v204, 16, v157
	v_add_f32_e32 v2, 1.0, v2
	v_rcp_f32_e32 v156, v2
	v_add_f32_e32 v2, 1.0, v5
	v_and_b32_e32 v205, 0xffff0000, v157
	v_mul_f32_e32 v5, 0xbfb8aa3b, v204
	v_pk_mul_f32 v[158:159], v[164:165], v[158:159]
	s_waitcnt lgkmcnt(1)
	v_lshlrev_b32_e32 v164, 16, v112
	v_and_b32_e32 v165, 0xffff0000, v112
	v_exp_f32_e32 v5, v5
	v_mul_f32_e32 v112, 0xbfb8aa3b, v205
	v_exp_f32_e32 v112, v112
	v_mov_b32_e32 v130, v129
	v_mov_b32_e32 v134, v133
	v_pk_add_f32 v[130:131], v[130:131], v[134:135]
	v_mov_b32_e32 v133, v136
	v_mov_b32_e32 v132, v130
	v_mov_b32_e32 v136, v131
	v_rcp_f32_e32 v157, v2
	v_add_f32_e32 v2, 1.0, v5
	v_pk_add_f32 v[130:131], v[132:133], v[136:137]
	v_rcp_f32_e32 v206, v2
	v_add_f32_e32 v2, 1.0, v112
	v_pk_fma_f32 v[122:123], v[130:131], s[14:15], v[122:123] op_sel_hi:[1,0,0]
	v_rcp_f32_e32 v207, v2
	v_mul_f32_e32 v2, 0x4b800000, v123
	v_cmp_gt_f32_e32 vcc, s51, v123
	v_lshlrev_b32_e32 v168, 16, v110
	v_and_b32_e32 v169, 0xffff0000, v110
	v_cndmask_b32_e32 v2, v123, v2, vcc
	v_rsq_f32_e32 v2, v2
	v_lshlrev_b32_e32 v110, 16, v111
	v_and_b32_e32 v111, 0xffff0000, v111
	v_lshlrev_b32_e32 v112, 16, v113
	v_mul_f32_e32 v5, 0x45800000, v2
	v_cndmask_b32_e32 v2, v2, v5, vcc
	v_pk_mul_f32 v[130:131], v[2:3], v[168:169] op_sel_hi:[0,1]
	v_pk_mul_f32 v[110:111], v[2:3], v[110:111] op_sel_hi:[0,1]
	v_pk_mul_f32 v[102:103], v[102:103], v[130:131]
	v_pk_mul_f32 v[104:105], v[104:105], v[110:111]
	v_pk_mul_f32 v[102:103], v[160:161], v[102:103]
	v_pk_mul_f32 v[104:105], v[158:159], v[104:105]
	v_and_b32_e32 v113, 0xffff0000, v113
	v_cvt_pk_bf16_f32 v102, v102, v103
	v_cvt_pk_bf16_f32 v103, v104, v105
	v_pk_mul_f32 v[104:105], v[2:3], v[164:165] op_sel_hi:[0,1]
	v_pk_mul_f32 v[104:105], v[106:107], v[104:105]
	v_pk_mul_f32 v[106:107], v[2:3], v[112:113] op_sel_hi:[0,1]
	v_mul_f32_e32 v2, 0x4b800000, v122
	v_cmp_gt_f32_e32 vcc, s51, v122
	v_add_u32_e32 v128, 32, v4
	v_pk_mul_f32 v[156:157], v[156:157], v[170:171]
	v_cndmask_b32_e32 v2, v122, v2, vcc
	v_rsq_f32_e32 v2, v2
	v_pk_mul_f32 v[170:171], v[206:207], v[204:205]
	v_ashrrev_i32_e32 v129, 31, v128
	v_pk_mul_f32 v[106:107], v[108:109], v[106:107]
	v_lshlrev_b64 v[128:129], 11, v[128:129]
	v_pk_mul_f32 v[104:105], v[156:157], v[104:105]
	v_pk_mul_f32 v[106:107], v[170:171], v[106:107]
	v_lshl_add_u64 v[128:129], v[150:151], 0, v[128:129]
	v_cvt_pk_bf16_f32 v104, v104, v105
	v_cvt_pk_bf16_f32 v105, v106, v107
	global_store_dwordx4 v[128:129], v[102:105], off
	v_mul_f32_e32 v5, 0x45800000, v2
	v_cndmask_b32_e32 v2, v2, v5, vcc
	v_lshlrev_b32_e32 v102, 16, v154
	v_mul_f32_e32 v5, 0xbfb8aa3b, v102
	v_and_b32_e32 v103, 0xffff0000, v154
	v_exp_f32_e32 v5, v5
	v_mul_f32_e32 v104, 0xbfb8aa3b, v103
	v_exp_f32_e32 v105, v104
	s_waitcnt lgkmcnt(0)
	v_lshlrev_b32_e32 v106, 16, v124
	v_add_f32_e32 v5, 1.0, v5
	v_rcp_f32_e32 v104, v5
	v_add_f32_e32 v5, 1.0, v105
	v_rcp_f32_e32 v105, v5
	v_and_b32_e32 v107, 0xffff0000, v124
	v_pk_mul_f32 v[106:107], v[2:3], v[106:107] op_sel_hi:[0,1]
	v_pk_mul_f32 v[106:107], v[118:119], v[106:107]
	v_pk_mul_f32 v[102:103], v[104:105], v[102:103]
	v_lshlrev_b32_e32 v104, 16, v155
	v_pk_mul_f32 v[102:103], v[102:103], v[106:107]
	v_mul_f32_e32 v5, 0xbfb8aa3b, v104
	v_and_b32_e32 v105, 0xffff0000, v155
	v_cvt_pk_bf16_f32 v102, v102, v103
	v_exp_f32_e32 v5, v5
	v_mul_f32_e32 v103, 0xbfb8aa3b, v105
	v_exp_f32_e32 v103, v103
	v_lshlrev_b32_e32 v108, 16, v125
	v_add_f32_e32 v5, 1.0, v5
	v_rcp_f32_e32 v106, v5
	v_add_f32_e32 v5, 1.0, v103
	v_rcp_f32_e32 v107, v5
	v_and_b32_e32 v109, 0xffff0000, v125
	v_pk_mul_f32 v[108:109], v[2:3], v[108:109] op_sel_hi:[0,1]
	v_pk_mul_f32 v[108:109], v[120:121], v[108:109]
	v_pk_mul_f32 v[104:105], v[106:107], v[104:105]
	v_lshlrev_b32_e32 v110, 16, v127
	v_pk_mul_f32 v[104:105], v[104:105], v[108:109]
	v_lshlrev_b32_e32 v108, 16, v126
	v_cvt_pk_bf16_f32 v103, v104, v105
	v_lshlrev_b32_e32 v104, 16, v152
	v_mul_f32_e32 v5, 0xbfb8aa3b, v104
	v_and_b32_e32 v105, 0xffff0000, v152
	v_exp_f32_e32 v5, v5
	v_mul_f32_e32 v106, 0xbfb8aa3b, v105
	v_exp_f32_e32 v107, v106
	v_and_b32_e32 v109, 0xffff0000, v126
	v_add_f32_e32 v5, 1.0, v5
	v_rcp_f32_e32 v106, v5
	v_add_f32_e32 v5, 1.0, v107
	v_rcp_f32_e32 v107, v5
	v_pk_mul_f32 v[108:109], v[2:3], v[108:109] op_sel_hi:[0,1]
	v_pk_mul_f32 v[108:109], v[114:115], v[108:109]
	v_and_b32_e32 v111, 0xffff0000, v127
	v_pk_mul_f32 v[104:105], v[106:107], v[104:105]
	v_lshlrev_b32_e32 v106, 16, v153
	v_pk_mul_f32 v[104:105], v[104:105], v[108:109]
	v_mul_f32_e32 v5, 0xbfb8aa3b, v106
	v_and_b32_e32 v107, 0xffff0000, v153
	v_cvt_pk_bf16_f32 v104, v104, v105
	v_exp_f32_e32 v5, v5
	v_mul_f32_e32 v105, 0xbfb8aa3b, v107
	v_exp_f32_e32 v105, v105
	v_pk_mul_f32 v[110:111], v[2:3], v[110:111] op_sel_hi:[0,1]
	v_add_f32_e32 v5, 1.0, v5
	v_rcp_f32_e32 v108, v5
	v_add_f32_e32 v5, 1.0, v105
	v_rcp_f32_e32 v109, v5
	v_add_u32_e32 v4, 48, v4
	v_pk_mul_f32 v[110:111], v[116:117], v[110:111]
	v_ashrrev_i32_e32 v5, 31, v4
	v_pk_mul_f32 v[106:107], v[108:109], v[106:107]
	v_lshlrev_b64 v[4:5], 11, v[4:5]
	v_pk_mul_f32 v[106:107], v[106:107], v[110:111]
	v_lshl_add_u64 v[4:5], v[150:151], 0, v[4:5]
	v_cvt_pk_bf16_f32 v105, v106, v107
	global_store_dwordx4 v[4:5], v[102:105], off
.LBB0_445:
	s_add_i32 s58, s29, 1
	s_cmpk_lg_i32 s56, 0xfc0
	s_cselect_b32 s31, s58, 63
	s_add_u32 s38, s34, s31
	s_addc_u32 s39, s35, 0
	s_and_b64 s[0:1], s[24:25], exec
	s_cselect_b32 s0, s31, s29
	s_mul_hi_u32 s1, s26, s0
	s_mul_i32 s0, s26, s0
	v_lshl_add_u64 v[4:5], s[0:1], 1, v[162:163]
	s_mov_b32 s29, s9
	v_lshl_add_u64 v[102:103], v[4:5], 0, s[8:9]
	v_lshl_add_u64 v[104:105], v[4:5], 0, s[28:29]
	s_mov_b32 s37, s9
	s_mov_b32 s31, s9
	v_lshl_add_u64 v[106:107], v[104:105], 0, s[8:9]
	global_load_dwordx2 v[170:171], v[4:5], off
	global_load_dwordx2 v[168:169], v[102:103], off
	global_load_dwordx2 v[164:165], v[104:105], off
	global_load_dwordx2 v[160:161], v[106:107], off
	v_lshl_add_u64 v[102:103], v[4:5], 0, s[36:37]
	v_lshl_add_u64 v[4:5], v[4:5], 0, s[30:31]
	v_lshl_add_u64 v[104:105], v[102:103], 0, s[8:9]
	v_lshl_add_u64 v[106:107], v[4:5], 0, s[8:9]
	global_load_dwordx2 v[158:159], v[102:103], off
	global_load_dwordx2 v[156:157], v[104:105], off
	global_load_dwordx2 v[154:155], v[4:5], off
	global_load_dwordx2 v[152:153], v[106:107], off
	s_and_b64 vcc, exec, s[6:7]
	s_cbranch_vccnz .LBB0_447
	s_lshl_b64 s[0:1], s[38:39], 2
	s_add_u32 s0, s41, s0
	s_addc_u32 s1, s42, s1
	global_load_dword v147, v3, s[0:1]
